# 64-step chain: next chunk's decay/staging/UT loads issued at the start of stage C of the current chunk (cross-chunk software prefetch), chunk top only waits and writes LDS
# speedup vs baseline: 1.0176x; 1.0042x over previous
.LBB0_1098:
	s_lshl_b32 s10, s0, 4
	s_add_i32 s10, s1, s10
	s_ashr_i32 s11, s10, 31
	s_mul_i32 s29, s10, 0x12000
	s_mul_hi_i32 s26, s10, 0x12000
	s_add_u32 s30, s19, s29
	s_addc_u32 s31, s42, s26
	s_lshl_b64 s[10:11], s[10:11], 2
	s_add_u32 s10, s43, s10
	s_addc_u32 s11, s4, s11
	s_cmp_lg_u32 s0, 0
	s_cbranch_scc1 .Lck64_ldskip
	global_load_dword v228, v125, s[10:11] sc1
	v_add_u32_e32 v40, 0x2000, v113
	v_add_u32_e32 v41, 0x8000, v113
	v_add_u32_e32 v38, 0xa000, v113
	v_add_u32_e32 v39, 0xc000, v113
	v_add_u32_e32 v34, 0xe000, v113
	v_add_u32_e32 v35, 0x10000, v113
	global_load_dwordx4 v[166:169], v113, s[30:31]
	global_load_dwordx4 v[170:173], v40, s[30:31]
	global_load_dwordx4 v[174:177], v41, s[30:31]
	global_load_dwordx4 v[178:181], v38, s[30:31]
	global_load_dwordx4 v[182:185], v39, s[30:31]
	global_load_dwordx4 v[186:189], v34, s[30:31]
	global_load_dwordx4 v[190:193], v35, s[30:31]
	v_lshl_add_u64 v[226:227], s[30:31], 0, v[72:73]
	v_lshl_add_u64 v[226:227], v[226:227], 0, v[68:69]
	s_mov_b64 s[10:11], 0x4000
	v_lshl_add_u64 v[226:227], v[226:227], 0, s[10:11]
	global_load_dwordx2 v[214:215], v[226:227], off
	global_load_dwordx2 v[216:217], v[226:227], off offset:32
	global_load_dwordx2 v[218:219], v[226:227], off offset:64
	global_load_dwordx2 v[220:221], v[226:227], off offset:96
.Lck64_ldskip:
	v_ashrrev_i32_e32 v32, 4, v67
	v_mul_u32_u24_e32 v32, 0x110, v32
	v_and_b32_e32 v33, 15, v67
	v_lshl_add_u32 v32, v33, 4, v32
	v_ashrrev_i32_e32 v33, 3, v67
	v_lshl_add_u32 v33, v33, 4, v113
	s_waitcnt lgkmcnt(0)
	s_barrier
	s_waitcnt vmcnt(10)
	v_mov_b32_e32 v56, v228
	ds_write_b128 v32, v[166:169] offset:0
	s_waitcnt vmcnt(9)
	ds_write_b128 v32, v[170:173] offset:8704
	s_waitcnt vmcnt(8)
	ds_write_b128 v32, v[174:177] offset:17408
	s_waitcnt vmcnt(7)
	ds_write_b128 v32, v[178:181] offset:26112
	s_waitcnt vmcnt(6)
	ds_write_b128 v33, v[182:185] offset:34816
	s_waitcnt vmcnt(5)
	ds_write_b128 v33, v[186:189] offset:44032
	s_waitcnt vmcnt(4)
	ds_write_b128 v33, v[190:193] offset:53248
	v_add_u32_e32 v57, v110, v68
	v_add_u32_e32 v36, v66, v109
	s_waitcnt lgkmcnt(0)
	s_barrier
	ds_read_b128 v[52:55], v36 offset:62464
	ds_read_b128 v[48:51], v36 offset:62528
	ds_read_b128 v[44:47], v36 offset:62592
	ds_read_b128 v[40:43], v36 offset:62656
	ds_read_b128 v[138:141], v114 offset:0
	ds_read_b128 v[142:145], v114 offset:64
	ds_read_b128 v[146:149], v114 offset:128
	ds_read_b128 v[150:153], v114 offset:192
	ds_read_b128 v[194:197], v114 offset:4352
	ds_read_b128 v[198:201], v114 offset:4416
	ds_read_b128 v[202:205], v114 offset:4480
	ds_read_b128 v[206:209], v114 offset:4544
	s_waitcnt lgkmcnt(7)
	v_mfma_f32_16x16x32_bf16 v[154:157], v[138:141], v[52:55], 0
	s_waitcnt lgkmcnt(6)
	v_mfma_f32_16x16x32_bf16 v[154:157], v[142:145], v[48:51], v[154:157]
	s_waitcnt lgkmcnt(5)
	v_mfma_f32_16x16x32_bf16 v[154:157], v[146:149], v[44:47], v[154:157]
	s_waitcnt lgkmcnt(4)
	v_mfma_f32_16x16x32_bf16 v[154:157], v[150:153], v[40:43], v[154:157]
	ds_read_b128 v[138:141], v114 offset:8704
	ds_read_b128 v[142:145], v114 offset:8768
	ds_read_b128 v[146:149], v114 offset:8832
	ds_read_b128 v[150:153], v114 offset:8896
	s_waitcnt lgkmcnt(7)
	v_mfma_f32_16x16x32_bf16 v[210:213], v[194:197], v[52:55], 0
	s_waitcnt lgkmcnt(6)
	v_mfma_f32_16x16x32_bf16 v[210:213], v[198:201], v[48:51], v[210:213]
	s_waitcnt lgkmcnt(5)
	v_mfma_f32_16x16x32_bf16 v[210:213], v[202:205], v[44:47], v[210:213]
	s_waitcnt lgkmcnt(4)
	v_mfma_f32_16x16x32_bf16 v[210:213], v[206:209], v[40:43], v[210:213]
	s_waitcnt vmcnt(3)
	v_lshlrev_b32_e32 v222, 16, v214
	v_and_b32_e32 v223, 0xffff0000, v214
	v_lshlrev_b32_e32 v224, 16, v215
	v_and_b32_e32 v225, 0xffff0000, v215
	v_pk_add_f32 v[154:155], v[222:223], v[154:155] neg_lo:[0,1] neg_hi:[0,1]
	v_pk_add_f32 v[156:157], v[224:225], v[156:157] neg_lo:[0,1] neg_hi:[0,1]
	v_cvt_pk_bf16_f32 v154, v154, v155
	v_cvt_pk_bf16_f32 v155, v156, v157
	ds_write_b64 v57, v[154:155]
	ds_read_b128 v[194:197], v114 offset:13056
	ds_read_b128 v[198:201], v114 offset:13120
	ds_read_b128 v[202:205], v114 offset:13184
	ds_read_b128 v[206:209], v114 offset:13248
	s_waitcnt lgkmcnt(8)
	v_mfma_f32_16x16x32_bf16 v[154:157], v[138:141], v[52:55], 0
	s_waitcnt lgkmcnt(7)
	v_mfma_f32_16x16x32_bf16 v[154:157], v[142:145], v[48:51], v[154:157]
	s_waitcnt lgkmcnt(6)
	v_mfma_f32_16x16x32_bf16 v[154:157], v[146:149], v[44:47], v[154:157]
	s_waitcnt lgkmcnt(5)
	v_mfma_f32_16x16x32_bf16 v[154:157], v[150:153], v[40:43], v[154:157]
	s_waitcnt vmcnt(2)
	v_lshlrev_b32_e32 v222, 16, v216
	v_and_b32_e32 v223, 0xffff0000, v216
	v_lshlrev_b32_e32 v224, 16, v217
	v_and_b32_e32 v225, 0xffff0000, v217
	v_pk_add_f32 v[210:211], v[222:223], v[210:211] neg_lo:[0,1] neg_hi:[0,1]
	v_pk_add_f32 v[212:213], v[224:225], v[212:213] neg_lo:[0,1] neg_hi:[0,1]
	v_cvt_pk_bf16_f32 v210, v210, v211
	v_cvt_pk_bf16_f32 v211, v212, v213
	ds_write_b64 v57, v[210:211] offset:32
	s_waitcnt lgkmcnt(4)
	v_mfma_f32_16x16x32_bf16 v[210:213], v[194:197], v[52:55], 0
	s_waitcnt lgkmcnt(3)
	v_mfma_f32_16x16x32_bf16 v[210:213], v[198:201], v[48:51], v[210:213]
	s_waitcnt lgkmcnt(2)
	v_mfma_f32_16x16x32_bf16 v[210:213], v[202:205], v[44:47], v[210:213]
	s_waitcnt lgkmcnt(1)
	v_mfma_f32_16x16x32_bf16 v[210:213], v[206:209], v[40:43], v[210:213]
	s_waitcnt vmcnt(1)
	v_lshlrev_b32_e32 v222, 16, v218
	v_and_b32_e32 v223, 0xffff0000, v218
	v_lshlrev_b32_e32 v224, 16, v219
	v_and_b32_e32 v225, 0xffff0000, v219
	v_pk_add_f32 v[154:155], v[222:223], v[154:155] neg_lo:[0,1] neg_hi:[0,1]
	v_pk_add_f32 v[156:157], v[224:225], v[156:157] neg_lo:[0,1] neg_hi:[0,1]
	v_cvt_pk_bf16_f32 v154, v154, v155
	v_cvt_pk_bf16_f32 v155, v156, v157
	ds_write_b64 v57, v[154:155] offset:64
	s_nop 1
	s_waitcnt vmcnt(0)
	v_lshlrev_b32_e32 v222, 16, v220
	v_and_b32_e32 v223, 0xffff0000, v220
	v_lshlrev_b32_e32 v224, 16, v221
	v_and_b32_e32 v225, 0xffff0000, v221
	v_pk_add_f32 v[210:211], v[222:223], v[210:211] neg_lo:[0,1] neg_hi:[0,1]
	v_pk_add_f32 v[212:213], v[224:225], v[212:213] neg_lo:[0,1] neg_hi:[0,1]
	v_cvt_pk_bf16_f32 v210, v210, v211
	v_cvt_pk_bf16_f32 v211, v212, v213
	ds_write_b64 v57, v[210:211] offset:96
	v_add_u32_e32 v226, v110, v109
	s_waitcnt lgkmcnt(0)
	s_barrier
	ds_read_b128 v[36:39], v226
	ds_read_b128 v[32:35], v226 offset:64
	ds_read_b128 v[138:141], v114 offset:17408
	ds_read_b128 v[142:145], v114 offset:17472
	ds_read_b128 v[146:149], v114 offset:17536
	ds_read_b128 v[150:153], v114 offset:17600
	ds_read_b128 v[154:157], v115 offset:34816
	ds_read_b128 v[194:197], v115 offset:34880
	ds_read_b128 v[198:201], v114 offset:21760
	ds_read_b128 v[202:205], v114 offset:21824
	ds_read_b128 v[206:209], v114 offset:21888
	ds_read_b128 v[210:213], v114 offset:21952
	ds_read_b128 v[214:217], v115 offset:37120
	ds_read_b128 v[218:221], v115 offset:37184
	s_waitcnt lgkmcnt(11)
	v_mfma_f32_16x16x32_bf16 v[222:225], v[138:141], v[52:55], 0
	s_waitcnt lgkmcnt(10)
	v_mfma_f32_16x16x32_bf16 v[222:225], v[142:145], v[48:51], v[222:225]
	s_waitcnt lgkmcnt(9)
	v_mfma_f32_16x16x32_bf16 v[222:225], v[146:149], v[44:47], v[222:225]
	s_waitcnt lgkmcnt(8)
	v_mfma_f32_16x16x32_bf16 v[222:225], v[150:153], v[40:43], v[222:225]
	s_waitcnt lgkmcnt(7)
	v_mfma_f32_16x16x32_bf16 v[222:225], v[154:157], v[36:39], v[222:225]
	s_waitcnt lgkmcnt(6)
	v_mfma_f32_16x16x32_bf16 v[222:225], v[194:197], v[32:35], v[222:225]
	ds_read_b128 v[138:141], v114 offset:26112
	ds_read_b128 v[142:145], v114 offset:26176
	ds_read_b128 v[146:149], v114 offset:26240
	ds_read_b128 v[150:153], v114 offset:26304
	ds_read_b128 v[154:157], v115 offset:39424
	ds_read_b128 v[194:197], v115 offset:39488
	s_waitcnt lgkmcnt(11)
	v_mfma_f32_16x16x32_bf16 v[244:247], v[198:201], v[52:55], 0
	s_waitcnt lgkmcnt(10)
	v_mfma_f32_16x16x32_bf16 v[244:247], v[202:205], v[48:51], v[244:247]
	s_waitcnt lgkmcnt(9)
	v_mfma_f32_16x16x32_bf16 v[244:247], v[206:209], v[44:47], v[244:247]
	s_waitcnt lgkmcnt(8)
	v_mfma_f32_16x16x32_bf16 v[244:247], v[210:213], v[40:43], v[244:247]
	s_waitcnt lgkmcnt(7)
	v_mfma_f32_16x16x32_bf16 v[244:247], v[214:217], v[36:39], v[244:247]
	s_waitcnt lgkmcnt(6)
	v_mfma_f32_16x16x32_bf16 v[244:247], v[218:221], v[32:35], v[244:247]
	ds_read_b128 v[198:201], v114 offset:30464
	ds_read_b128 v[202:205], v114 offset:30528
	ds_read_b128 v[206:209], v114 offset:30592
	ds_read_b128 v[210:213], v114 offset:30656
	ds_read_b128 v[214:217], v115 offset:41728
	ds_read_b128 v[218:221], v115 offset:41792
	s_waitcnt lgkmcnt(11)
	v_mfma_f32_16x16x32_bf16 v[248:251], v[138:141], v[52:55], 0
	s_waitcnt lgkmcnt(10)
	v_mfma_f32_16x16x32_bf16 v[248:251], v[142:145], v[48:51], v[248:251]
	s_waitcnt lgkmcnt(9)
	v_mfma_f32_16x16x32_bf16 v[248:251], v[146:149], v[44:47], v[248:251]
	s_waitcnt lgkmcnt(8)
	v_mfma_f32_16x16x32_bf16 v[248:251], v[150:153], v[40:43], v[248:251]
	s_waitcnt lgkmcnt(7)
	v_mfma_f32_16x16x32_bf16 v[248:251], v[154:157], v[36:39], v[248:251]
	s_waitcnt lgkmcnt(6)
	v_mfma_f32_16x16x32_bf16 v[248:251], v[194:197], v[32:35], v[248:251]
	v_cvt_pk_bf16_f32 v57, v222, s0
	ds_write_b16 v116, v57
	v_cvt_pk_bf16_f32 v57, v223, s0
	ds_write_b16 v117, v57
	v_cvt_pk_bf16_f32 v57, v224, s0
	ds_write_b16 v117, v57 offset:272
	v_cvt_pk_bf16_f32 v57, v225, s0
	ds_write_b16 v117, v57 offset:544
	v_cvt_pk_bf16_f32 v57, v244, s0
	ds_write_b16 v117, v57 offset:4080
	v_cvt_pk_bf16_f32 v57, v245, s0
	ds_write_b16 v117, v57 offset:4352
	v_cvt_pk_bf16_f32 v57, v246, s0
	ds_write_b16 v117, v57 offset:4624
	v_cvt_pk_bf16_f32 v57, v247, s0
	ds_write_b16 v117, v57 offset:4896
	v_pk_mul_f32 v[30:31], v[30:31], v[56:57] op_sel_hi:[1,0]
	v_pk_mul_f32 v[28:29], v[28:29], v[56:57] op_sel_hi:[1,0]
	v_pk_mul_f32 v[22:23], v[22:23], v[56:57] op_sel_hi:[1,0]
	v_pk_mul_f32 v[20:21], v[20:21], v[56:57] op_sel_hi:[1,0]
	v_pk_mul_f32 v[2:3], v[2:3], v[56:57] op_sel_hi:[1,0]
	v_pk_mul_f32 v[0:1], v[0:1], v[56:57] op_sel_hi:[1,0]
	v_pk_mul_f32 v[18:19], v[18:19], v[56:57] op_sel_hi:[1,0]
	v_pk_mul_f32 v[16:17], v[16:17], v[56:57] op_sel_hi:[1,0]
	v_pk_mul_f32 v[6:7], v[6:7], v[56:57] op_sel_hi:[1,0]
	v_pk_mul_f32 v[4:5], v[4:5], v[56:57] op_sel_hi:[1,0]
	v_mul_f32_e64 v14, v14, v56
	v_mul_f32_e64 v15, v15, v56
	v_pk_mul_f32 v[12:13], v[12:13], v[56:57] op_sel_hi:[1,0]
	v_pk_mul_f32 v[10:11], v[10:11], v[56:57] op_sel_hi:[1,0]
	v_pk_mul_f32 v[8:9], v[8:9], v[56:57] op_sel_hi:[1,0]
	v_pk_mul_f32 v[26:27], v[26:27], v[56:57] op_sel_hi:[1,0]
	v_pk_mul_f32 v[24:25], v[24:25], v[56:57] op_sel_hi:[1,0]
	s_waitcnt lgkmcnt(13)
	v_mfma_f32_16x16x32_bf16 v[222:225], v[198:201], v[52:55], 0
	s_waitcnt lgkmcnt(12)
	v_mfma_f32_16x16x32_bf16 v[222:225], v[202:205], v[48:51], v[222:225]
	s_waitcnt lgkmcnt(11)
	v_mfma_f32_16x16x32_bf16 v[222:225], v[206:209], v[44:47], v[222:225]
	s_waitcnt lgkmcnt(10)
	v_mfma_f32_16x16x32_bf16 v[222:225], v[210:213], v[40:43], v[222:225]
	s_waitcnt lgkmcnt(9)
	v_mfma_f32_16x16x32_bf16 v[222:225], v[214:217], v[36:39], v[222:225]
	s_waitcnt lgkmcnt(8)
	v_mfma_f32_16x16x32_bf16 v[222:225], v[218:221], v[32:35], v[222:225]
	v_cvt_pk_bf16_f32 v57, v248, s0
	ds_write_b16 v117, v57 offset:8432
	v_cvt_pk_bf16_f32 v57, v249, s0
	ds_write_b16 v117, v57 offset:8704
	v_cvt_pk_bf16_f32 v57, v250, s0
	ds_write_b16 v117, v57 offset:8976
	v_cvt_pk_bf16_f32 v57, v251, s0
	ds_write_b16 v117, v57 offset:9248
	s_cmp_eq_u32 s0, 31
	s_cbranch_scc1 .Lck64_nopf
	s_add_i32 s98, s0, 1
	s_lshl_b32 s98, s98, 4
	s_add_i32 s98, s1, s98
	s_ashr_i32 s99, s98, 31
	s_mul_i32 s100, s98, 0x12000
	s_mul_hi_i32 s101, s98, 0x12000
	s_add_u32 s100, s19, s100
	s_addc_u32 s101, s42, s101
	s_lshl_b64 s[98:99], s[98:99], 2
	s_add_u32 s98, s43, s98
	s_addc_u32 s99, s4, s99
	global_load_dword v228, v125, s[98:99] sc1
	v_add_u32_e32 v206, 0x2000, v113
	v_add_u32_e32 v207, 0x8000, v113
	v_add_u32_e32 v208, 0xa000, v113
	v_add_u32_e32 v209, 0xc000, v113
	v_add_u32_e32 v210, 0xe000, v113
	v_add_u32_e32 v211, 0x10000, v113
	global_load_dwordx4 v[166:169], v113, s[100:101]
	global_load_dwordx4 v[170:173], v206, s[100:101]
	global_load_dwordx4 v[174:177], v207, s[100:101]
	global_load_dwordx4 v[178:181], v208, s[100:101]
	global_load_dwordx4 v[182:185], v209, s[100:101]
	global_load_dwordx4 v[186:189], v210, s[100:101]
	global_load_dwordx4 v[190:193], v211, s[100:101]
	v_lshl_add_u64 v[212:213], s[100:101], 0, v[72:73]
	v_lshl_add_u64 v[212:213], v[212:213], 0, v[68:69]
	s_mov_b64 s[10:11], 0x4000
	v_lshl_add_u64 v[212:213], v[212:213], 0, s[10:11]
	global_load_dwordx2 v[214:215], v[212:213], off
	global_load_dwordx2 v[216:217], v[212:213], off offset:32
	global_load_dwordx2 v[218:219], v[212:213], off offset:64
	global_load_dwordx2 v[220:221], v[212:213], off offset:96
.Lck64_nopf:
	ds_read_b128 v[138:141], v115 offset:44032
	ds_read_b128 v[142:145], v115 offset:44096
	ds_read_b128 v[146:149], v115 offset:46336
	ds_read_b128 v[150:153], v115 offset:46400
	ds_read_b128 v[154:157], v115 offset:48640
	ds_read_b128 v[194:197], v115 offset:48704
	ds_read_b128 v[198:201], v115 offset:50944
	ds_read_b128 v[202:205], v115 offset:51008
	v_cvt_pk_bf16_f32 v57, v222, s0
	ds_write_b16 v117, v57 offset:12784
	v_cvt_pk_bf16_f32 v57, v223, s0
	ds_write_b16 v117, v57 offset:13056
	v_cvt_pk_bf16_f32 v57, v224, s0
	ds_write_b16 v117, v57 offset:13328
	v_cvt_pk_bf16_f32 v57, v225, s0
	ds_write_b16 v117, v57 offset:13600
	s_waitcnt lgkmcnt(11)
	v_mfma_f32_16x16x32_bf16 v[28:31], v[138:141], v[36:39], v[28:31]
	s_waitcnt lgkmcnt(10)
	v_mfma_f32_16x16x32_bf16 v[28:31], v[142:145], v[32:35], v[28:31]
	ds_read_b128 v[138:141], v115 offset:53248
	ds_read_b128 v[142:145], v115 offset:53312
	s_waitcnt lgkmcnt(11)
	v_mfma_f32_16x16x32_bf16 v[20:23], v[146:149], v[36:39], v[20:23]
	s_waitcnt lgkmcnt(10)
	v_mfma_f32_16x16x32_bf16 v[20:23], v[150:153], v[32:35], v[20:23]
	ds_read_b128 v[146:149], v115 offset:55552
	ds_read_b128 v[150:153], v115 offset:55616
	s_waitcnt lgkmcnt(11)
	v_mfma_f32_16x16x32_bf16 v[0:3], v[154:157], v[36:39], v[0:3]
	s_waitcnt lgkmcnt(10)
	v_mfma_f32_16x16x32_bf16 v[0:3], v[194:197], v[32:35], v[0:3]
	ds_read_b128 v[154:157], v115 offset:57856
	ds_read_b128 v[194:197], v115 offset:57920
	s_waitcnt lgkmcnt(11)
	v_mfma_f32_16x16x32_bf16 v[16:19], v[198:201], v[36:39], v[16:19]
	s_waitcnt lgkmcnt(10)
	v_mfma_f32_16x16x32_bf16 v[16:19], v[202:205], v[32:35], v[16:19]
	ds_read_b128 v[198:201], v115 offset:60160
	ds_read_b128 v[202:205], v115 offset:60224
	s_waitcnt lgkmcnt(7)
	v_mfma_f32_16x16x32_bf16 v[4:7], v[138:141], v[36:39], v[4:7]
	s_waitcnt lgkmcnt(6)
	v_mfma_f32_16x16x32_bf16 v[4:7], v[142:145], v[32:35], v[4:7]
	s_waitcnt lgkmcnt(5)
	v_mfma_f32_16x16x32_bf16 v[12:15], v[146:149], v[36:39], v[12:15]
	s_waitcnt lgkmcnt(4)
	v_mfma_f32_16x16x32_bf16 v[12:15], v[150:153], v[32:35], v[12:15]
	s_waitcnt lgkmcnt(3)
	v_mfma_f32_16x16x32_bf16 v[8:11], v[154:157], v[36:39], v[8:11]
	s_waitcnt lgkmcnt(2)
	v_mfma_f32_16x16x32_bf16 v[8:11], v[194:197], v[32:35], v[8:11]
	s_waitcnt lgkmcnt(1)
	v_mfma_f32_16x16x32_bf16 v[24:27], v[198:201], v[36:39], v[24:27]
	s_waitcnt lgkmcnt(0)
	s_waitcnt lgkmcnt(0)
	s_barrier
	v_mfma_f32_16x16x32_bf16 v[24:27], v[202:205], v[32:35], v[24:27]
	v_add_u32_e32 v36, v66, v68
	v_cvt_pk_bf16_f32 v32, v28, v29
	v_cvt_pk_bf16_f32 v33, v30, v31
	v_cvt_pk_bf16_f32 v34, v20, v21
	v_cvt_pk_bf16_f32 v35, v22, v23
	v_add_u32_e32 v36, 0xf000, v36
	ds_write2_b64 v36, v[32:33], v[34:35] offset0:128 offset1:132
	v_cvt_pk_bf16_f32 v32, v0, v1
	v_cvt_pk_bf16_f32 v33, v2, v3
	v_cvt_pk_bf16_f32 v34, v16, v17
	v_cvt_pk_bf16_f32 v35, v18, v19
	ds_write2_b64 v36, v[32:33], v[34:35] offset0:136 offset1:140
	v_cvt_pk_bf16_f32 v32, v4, v5
	v_cvt_pk_bf16_f32 v33, v6, v7
	v_cvt_pk_bf16_f32 v34, v12, v13
	v_cvt_pk_bf16_f32 v35, v14, v15
	ds_write2_b64 v36, v[32:33], v[34:35] offset0:144 offset1:148
	v_cvt_pk_bf16_f32 v32, v8, v9
	v_cvt_pk_bf16_f32 v33, v10, v11
	v_cvt_pk_bf16_f32 v34, v24, v25
	v_cvt_pk_bf16_f32 v35, v26, v27
	ds_write2_b64 v36, v[32:33], v[34:35] offset0:152 offset1:156
	s_and_saveexec_b64 s[30:31], s[40:41]
	s_cbranch_execz .LBB0_1097
	v_and_b32_e32 v32, 64, v164
	v_add_u32_e32 v32, 64, v32
	v_xor_b32_e32 v33, 1, v164
	v_cmp_lt_i32_e32 vcc, v33, v32
	ds_read_b128 v[52:55], v118
	ds_read_b128 v[60:63], v118 offset:16
	v_cndmask_b32_e32 v33, v164, v33, vcc
	v_lshlrev_b32_e32 v121, 2, v33
	v_xor_b32_e32 v33, 2, v164
	v_cmp_lt_i32_e32 vcc, v33, v32
	s_waitcnt lgkmcnt(0)
	v_lshlrev_b32_e32 v80, 16, v62
	v_and_b32_e32 v81, 0xffff0000, v62
	v_cndmask_b32_e32 v33, v164, v33, vcc
	v_lshlrev_b32_e32 v120, 2, v33
	v_xor_b32_e32 v33, 4, v164
	v_cmp_lt_i32_e32 vcc, v33, v32
	v_lshlrev_b32_e32 v78, 16, v63
	v_and_b32_e32 v79, 0xffff0000, v63
	v_cndmask_b32_e32 v32, v164, v33, vcc
	v_lshlrev_b32_e32 v119, 2, v32
	v_lshl_add_u32 v32, s0, 6, v112
	v_ashrrev_i32_e32 v33, 31, v32
	v_lshlrev_b64 v[76:77], 12, v[32:33]
	v_lshl_or_b32 v76, v70, 1, v76
	v_lshl_add_u64 v[32:33], s[46:47], 0, v[76:77]
	global_load_dwordx4 v[56:59], v[32:33], off
	s_nop 0
	global_load_dwordx4 v[32:35], v[32:33], off offset:16
	s_nop 0
	global_load_dwordx4 v[36:39], v[74:75], off offset:48
	global_load_dwordx4 v[40:43], v[74:75], off offset:32
	global_load_dwordx4 v[44:47], v[74:75], off offset:16
	global_load_dwordx4 v[48:51], v[74:75], off
	v_pk_mul_f32 v[62:63], v[80:81], v[80:81]
	v_pk_mul_f32 v[82:83], v[78:79], v[78:79]
	s_waitcnt vmcnt(5)
	v_lshlrev_b32_e32 v130, 16, v56
	s_waitcnt vmcnt(4)
	v_lshlrev_b32_e32 v84, 16, v34
	v_and_b32_e32 v85, 0xffff0000, v34
	v_mul_f32_e32 v34, 0xbfb8aa3b, v84
	v_exp_f32_e32 v86, v34
	v_mul_f32_e32 v34, 0xbfb8aa3b, v85
	v_exp_f32_e32 v87, v34
	v_and_b32_e32 v131, 0xffff0000, v56
	v_pk_add_f32 v[86:87], v[86:87], 1.0 op_sel_hi:[1,0]
	s_nop 0
	s_nop 0
	v_rcp_f32_e32 v87, v87
	s_nop 0
	s_nop 0
	v_lshlrev_b32_e32 v88, 16, v33
	v_and_b32_e32 v89, 0xffff0000, v33
	v_mul_f32_e32 v33, 0xbfb8aa3b, v88
	v_exp_f32_e32 v90, v33
	v_mul_f32_e32 v33, 0xbfb8aa3b, v89
	v_exp_f32_e32 v91, v33
	v_rcp_f32_e32 v86, v86
	s_nop 0
	v_pk_mul_f32 v[84:85], v[86:87], v[84:85]
	v_lshlrev_b32_e32 v86, 16, v61
	v_pk_add_f32 v[90:91], v[90:91], 1.0 op_sel_hi:[1,0]
	v_and_b32_e32 v87, 0xffff0000, v61
	v_pk_mul_f32 v[92:93], v[86:87], v[86:87]
	v_rcp_f32_e32 v91, v91
	s_nop 0
	s_nop 0
	v_lshlrev_b32_e32 v94, 16, v32
	v_and_b32_e32 v95, 0xffff0000, v32
	v_rcp_f32_e32 v90, v90
	s_nop 0
	v_mul_f32_e32 v32, 0xbfb8aa3b, v94
	v_mul_f32_e32 v33, 0xbfb8aa3b, v95
	v_exp_f32_e32 v32, v32
	v_exp_f32_e32 v33, v33
	v_pk_mul_f32 v[88:89], v[90:91], v[88:89]
	v_lshlrev_b32_e32 v90, 16, v60
	v_and_b32_e32 v91, 0xffff0000, v60
	v_pk_add_f32 v[32:33], v[32:33], 1.0 op_sel_hi:[1,0]
	v_pk_mul_f32 v[60:61], v[90:91], v[90:91]
	s_nop 0
	v_rcp_f32_e32 v33, v33
	s_nop 0
	s_nop 0
	v_lshlrev_b32_e32 v98, 16, v59
	v_rcp_f32_e32 v32, v32
	s_nop 0
	v_and_b32_e32 v99, 0xffff0000, v59
	v_mul_f32_e32 v34, 0xbfb8aa3b, v98
	v_exp_f32_e32 v100, v34
	v_mul_f32_e32 v34, 0xbfb8aa3b, v99
	v_exp_f32_e32 v101, v34
	v_pk_mul_f32 v[32:33], v[32:33], v[94:95]
	v_lshlrev_b32_e32 v94, 16, v55
	v_and_b32_e32 v95, 0xffff0000, v55
	v_pk_add_f32 v[100:101], v[100:101], 1.0 op_sel_hi:[1,0]
	v_pk_mul_f32 v[96:97], v[94:95], v[94:95]
	s_nop 0
	v_rcp_f32_e32 v101, v101
	s_nop 0
	s_nop 0
	v_lshlrev_b32_e32 v102, 16, v58
	v_rcp_f32_e32 v100, v100
	s_nop 0
	v_and_b32_e32 v103, 0xffff0000, v58
	v_mul_f32_e32 v34, 0xbfb8aa3b, v102
	v_exp_f32_e32 v58, v34
	v_mul_f32_e32 v34, 0xbfb8aa3b, v103
	v_exp_f32_e32 v59, v34
	v_pk_mul_f32 v[98:99], v[100:101], v[98:99]
	v_lshlrev_b32_e32 v100, 16, v54
	v_and_b32_e32 v101, 0xffff0000, v54
	v_pk_add_f32 v[58:59], v[58:59], 1.0 op_sel_hi:[1,0]
	v_pk_mul_f32 v[54:55], v[100:101], v[100:101]
	s_nop 0
	v_rcp_f32_e32 v59, v59
	s_nop 0
	s_nop 0
	v_lshlrev_b32_e32 v106, 16, v57
	v_rcp_f32_e32 v58, v58
	s_nop 0
	v_and_b32_e32 v107, 0xffff0000, v57
	v_mul_f32_e32 v34, 0xbfb8aa3b, v106
	v_exp_f32_e32 v122, v34
	v_mul_f32_e32 v34, 0xbfb8aa3b, v107
	v_exp_f32_e32 v123, v34
	v_pk_mul_f32 v[58:59], v[58:59], v[102:103]
	v_lshlrev_b32_e32 v102, 16, v53
	v_and_b32_e32 v103, 0xffff0000, v53
	v_pk_add_f32 v[122:123], v[122:123], 1.0 op_sel_hi:[1,0]
	v_pk_mul_f32 v[104:105], v[102:103], v[102:103]
	s_nop 0
	v_rcp_f32_e32 v123, v123
	s_nop 0
	s_nop 0
	v_rcp_f32_e32 v122, v122
	s_nop 0
	v_mul_f32_e32 v34, 0xbfb8aa3b, v130
	v_exp_f32_e32 v56, v34
	v_mul_f32_e32 v34, 0xbfb8aa3b, v131
	v_exp_f32_e32 v57, v34
	v_pk_mul_f32 v[106:107], v[122:123], v[106:107]
	v_lshlrev_b32_e32 v122, 16, v52
	v_and_b32_e32 v123, 0xffff0000, v52
	v_pk_add_f32 v[56:57], v[56:57], 1.0 op_sel_hi:[1,0]
	v_pk_mul_f32 v[52:53], v[122:123], v[122:123]
	s_nop 0
	v_rcp_f32_e32 v57, v57
	s_nop 0
	s_nop 0
	v_rcp_f32_e32 v56, v56
	s_nop 0
	v_add_f32_e32 v34, v52, v53
	v_add_f32_e32 v34, v104, v34
	v_add_f32_e32 v34, v105, v34
	v_add_f32_e32 v34, v54, v34
	v_add_f32_e32 v34, v55, v34
	v_add_f32_e32 v34, v96, v34
	v_add_f32_e32 v34, v97, v34
	v_add_f32_e32 v34, v60, v34
	v_add_f32_e32 v34, v61, v34
	v_add_f32_e32 v34, v92, v34
	v_add_f32_e32 v34, v93, v34
	v_add_f32_e32 v34, v62, v34
	v_add_f32_e32 v34, v63, v34
	v_add_f32_e32 v34, v82, v34
	v_add_f32_e32 v34, v83, v34
	ds_bpermute_b32 v52, v121, v34
	v_pk_mul_f32 v[56:57], v[56:57], v[130:131]
	s_waitcnt lgkmcnt(0)
	v_add_f32_e32 v34, v34, v52
	ds_bpermute_b32 v52, v120, v34
	s_waitcnt lgkmcnt(0)
	v_add_f32_e32 v34, v34, v52
	ds_bpermute_b32 v52, v119, v34
	s_waitcnt lgkmcnt(0)
	v_add_f32_e32 v34, v34, v52
	v_fmamk_f32 v34, v34, 0x3c000000, v162
	v_cmp_gt_f32_e32 vcc, s6, v34
	v_mul_f32_e32 v52, 0x4b800000, v34
	s_nop 0
	v_cndmask_b32_e32 v34, v34, v52, vcc
	v_rsq_f32_e32 v34, v34
	s_nop 0
	v_mul_f32_e32 v52, 0x45800000, v34
	v_cndmask_b32_e32 v52, v34, v52, vcc
	v_pk_mul_f32 v[54:55], v[52:53], v[122:123] op_sel_hi:[0,1]
	s_waitcnt vmcnt(0)
	v_pk_mul_f32 v[48:49], v[48:49], v[54:55]
	v_pk_mul_f32 v[54:55], v[52:53], v[102:103] op_sel_hi:[0,1]
	v_pk_mul_f32 v[50:51], v[50:51], v[54:55]
	v_pk_mul_f32 v[48:49], v[56:57], v[48:49]
	v_pk_mul_f32 v[50:51], v[106:107], v[50:51]
	v_cvt_pk_bf16_f32 v48, v48, v49
	v_cvt_pk_bf16_f32 v49, v50, v51
	v_pk_mul_f32 v[50:51], v[52:53], v[100:101] op_sel_hi:[0,1]
	v_pk_mul_f32 v[44:45], v[44:45], v[50:51]
	s_nop 0
	v_pk_mul_f32 v[44:45], v[58:59], v[44:45]
	s_nop 0
	v_cvt_pk_bf16_f32 v50, v44, v45
	v_pk_mul_f32 v[44:45], v[52:53], v[94:95] op_sel_hi:[0,1]
	v_pk_mul_f32 v[44:45], v[46:47], v[44:45]
	s_nop 0
	v_pk_mul_f32 v[44:45], v[98:99], v[44:45]
	s_nop 0
	v_cvt_pk_bf16_f32 v51, v44, v45
	v_pk_mul_f32 v[44:45], v[52:53], v[90:91] op_sel_hi:[0,1]
	v_pk_mul_f32 v[40:41], v[40:41], v[44:45]
	s_nop 0
	v_pk_mul_f32 v[32:33], v[32:33], v[40:41]
	v_pk_mul_f32 v[40:41], v[52:53], v[86:87] op_sel_hi:[0,1]
	v_pk_mul_f32 v[40:41], v[42:43], v[40:41]
	v_cvt_pk_bf16_f32 v32, v32, v33
	v_pk_mul_f32 v[40:41], v[88:89], v[40:41]
	v_pk_mul_f32 v[42:43], v[52:53], v[78:79] op_sel_hi:[0,1]
	v_cvt_pk_bf16_f32 v33, v40, v41
	v_pk_mul_f32 v[40:41], v[52:53], v[80:81] op_sel_hi:[0,1]
	v_pk_mul_f32 v[36:37], v[36:37], v[40:41]
	v_pk_mul_f32 v[38:39], v[38:39], v[42:43]
	v_pk_mul_f32 v[36:37], v[84:85], v[36:37]
	s_nop 0
	v_cvt_pk_bf16_f32 v34, v36, v37
	v_lshlrev_b32_e32 v36, 16, v35
	v_and_b32_e32 v37, 0xffff0000, v35
	v_mul_f32_e32 v35, 0xbfb8aa3b, v36
	v_exp_f32_e32 v40, v35
	v_mul_f32_e32 v35, 0xbfb8aa3b, v37
	v_exp_f32_e32 v41, v35
	s_nop 0
	v_pk_add_f32 v[40:41], v[40:41], 1.0 op_sel_hi:[1,0]
	s_nop 0
	s_nop 0
	v_rcp_f32_e32 v41, v41
	s_nop 0
	s_nop 0
	v_rcp_f32_e32 v40, v40
	s_nop 0
	v_pk_mul_f32 v[36:37], v[40:41], v[36:37]
	s_nop 0
	v_pk_mul_f32 v[36:37], v[36:37], v[38:39]
	s_nop 0
	v_cvt_pk_bf16_f32 v35, v36, v37
	v_lshl_add_u64 v[36:37], s[48:49], 0, v[76:77]
	global_store_dwordx4 v[36:37], v[48:51], off
	global_store_dwordx4 v[36:37], v[32:35], off offset:16
	s_branch .LBB0_1097
